# v74 plus in-projection plain-section epilogue: lanes transposed with ds_bpermute before the 16-byte stores so 8 consecutive lanes write one row's 128 contiguous bytes (coalescable quads) instead of 64
# speedup vs baseline: 1.0069x; 1.0069x over previous
.Lpeelx0:
	s_lshl_b32 s7, s34, 8
	s_cmp_lt_i32 s35, 28
	s_mov_b64 s[4:5], -1
	s_cbranch_scc0 .LBB0_431
	s_add_i32 s16, s7, s27
	v_or_b32_e32 v207, s16, v192
	s_cmp_gt_i32 s35, 3
	s_cbranch_scc0 .LBB0_411
	s_add_i32 s4, s35, -12
	s_cmp_gt_u32 s4, 7
	s_mov_b64 s[4:5], -1
	s_cbranch_scc0 .LBB0_408
	s_waitcnt lgkmcnt(0)
	s_lshl_b32 s4, s35, 8
	s_add_i32 s5, s4, 0xfffffc00
	s_cmp_lt_u32 s35, 12
	s_cselect_b32 s4, s4, s5
	v_and_b32_e32 v11, 8, v220
	v_cmp_ne_u32_e32 vcc, 0, v11
	v_bfe_u32 v10, v220, 3, 3
	v_and_b32_e32 v12, 0x60, v194
	v_lshlrev_b32_e32 v12, 1, v12
	v_and_b32_e32 v13, 7, v220
	v_lshl_or_b32 v12, v13, 3, v12
	v_or_b32_e32 v32, s4, v12
	v_or_b32_e32 v14, s16, v10
	v_mov_b64_e32 v[4:5], s[70:71]
	v_mad_i64_i32 v[0:1], s[4:5], v14, s33, v[4:5]
	v_lshlrev_b64 v[6:7], 1, v[32:33]
	v_lshl_add_u64 v[16:17], v[0:1], 0, v[6:7]
	v_and_b32_e32 v13, 4, v220
	v_lshl_or_b32 v13, v13, 1, v10
	v_and_b32_e32 v12, 3, v220
	v_lshl_or_b32 v13, v12, 4, v13
	v_lshlrev_b32_e32 v13, 2, v13
	v_mov_b32_e32 v32, 0x30000
	v_lshl_add_u64 v[18:19], v[16:17], 0, v[32:33]
	v_lshl_add_u64 v[20:21], v[18:19], 0, v[32:33]
	v_lshl_add_u64 v[22:23], v[20:21], 0, v[32:33]
	v_mov_b32_e32 v8, 0x180000
	v_mov_b32_e32 v9, 0
	v_lshl_add_u64 v[24:25], v[16:17], 0, v[8:9]
	v_lshl_add_u64 v[26:27], v[24:25], 0, v[32:33]
	v_lshl_add_u64 v[28:29], v[26:27], 0, v[32:33]
	v_lshl_add_u64 v[30:31], v[28:29], 0, v[32:33]
	v_mov_b32_e32 v8, 0x18000
	v_cvt_pk_f16_f32 v158, v158, v159
	v_cvt_pk_f16_f32 v159, v160, v161
	v_cvt_pk_f16_f32 v160, v142, v143
	v_cvt_pk_f16_f32 v161, v144, v145
	v_cvt_pk_f16_f32 v94, v94, v95
	v_cvt_pk_f16_f32 v95, v96, v97
	v_cvt_pk_f16_f32 v96, v78, v79
	v_cvt_pk_f16_f32 v97, v80, v81
	v_mov_b32_dpp v0, v158 row_ror:8 row_mask:0xf bank_mask:0xf
	v_mov_b32_dpp v1, v159 row_ror:8 row_mask:0xf bank_mask:0xf
	v_mov_b32_dpp v2, v160 row_ror:8 row_mask:0xf bank_mask:0xf
	v_mov_b32_dpp v3, v161 row_ror:8 row_mask:0xf bank_mask:0xf
	v_mov_b32_dpp v4, v94 row_ror:8 row_mask:0xf bank_mask:0xf
	v_mov_b32_dpp v5, v95 row_ror:8 row_mask:0xf bank_mask:0xf
	v_mov_b32_dpp v6, v96 row_ror:8 row_mask:0xf bank_mask:0xf
	v_mov_b32_dpp v7, v97 row_ror:8 row_mask:0xf bank_mask:0xf
	v_cndmask_b32_e32 v158, v158, v4, vcc
	v_cndmask_b32_e32 v159, v159, v5, vcc
	v_cndmask_b32_e32 v160, v160, v6, vcc
	v_cndmask_b32_e32 v161, v161, v7, vcc
	v_cndmask_b32_e32 v94, v0, v94, vcc
	v_cndmask_b32_e32 v95, v1, v95, vcc
	v_cndmask_b32_e32 v96, v2, v96, vcc
	v_cndmask_b32_e32 v97, v3, v97, vcc
	ds_bpermute_b32 v158, v13, v158
	ds_bpermute_b32 v159, v13, v159
	ds_bpermute_b32 v160, v13, v160
	ds_bpermute_b32 v161, v13, v161
	ds_bpermute_b32 v94, v13, v94
	ds_bpermute_b32 v95, v13, v95
	ds_bpermute_b32 v96, v13, v96
	ds_bpermute_b32 v97, v13, v97
	v_cvt_pk_f16_f32 v150, v150, v151
	v_cvt_pk_f16_f32 v151, v152, v153
	v_cvt_pk_f16_f32 v152, v134, v135
	v_cvt_pk_f16_f32 v153, v136, v137
	v_cvt_pk_f16_f32 v86, v86, v87
	v_cvt_pk_f16_f32 v87, v88, v89
	v_cvt_pk_f16_f32 v88, v70, v71
	v_cvt_pk_f16_f32 v89, v72, v73
	v_mov_b32_dpp v0, v150 row_ror:8 row_mask:0xf bank_mask:0xf
	v_mov_b32_dpp v1, v151 row_ror:8 row_mask:0xf bank_mask:0xf
	v_mov_b32_dpp v2, v152 row_ror:8 row_mask:0xf bank_mask:0xf
	v_mov_b32_dpp v3, v153 row_ror:8 row_mask:0xf bank_mask:0xf
	v_mov_b32_dpp v4, v86 row_ror:8 row_mask:0xf bank_mask:0xf
	v_mov_b32_dpp v5, v87 row_ror:8 row_mask:0xf bank_mask:0xf
	v_mov_b32_dpp v6, v88 row_ror:8 row_mask:0xf bank_mask:0xf
	v_mov_b32_dpp v7, v89 row_ror:8 row_mask:0xf bank_mask:0xf
	v_cndmask_b32_e32 v150, v150, v4, vcc
	v_cndmask_b32_e32 v151, v151, v5, vcc
	v_cndmask_b32_e32 v152, v152, v6, vcc
	v_cndmask_b32_e32 v153, v153, v7, vcc
	v_cndmask_b32_e32 v86, v0, v86, vcc
	v_cndmask_b32_e32 v87, v1, v87, vcc
	v_cndmask_b32_e32 v88, v2, v88, vcc
	v_cndmask_b32_e32 v89, v3, v89, vcc
	ds_bpermute_b32 v150, v13, v150
	ds_bpermute_b32 v151, v13, v151
	ds_bpermute_b32 v152, v13, v152
	ds_bpermute_b32 v153, v13, v153
	ds_bpermute_b32 v86, v13, v86
	ds_bpermute_b32 v87, v13, v87
	ds_bpermute_b32 v88, v13, v88
	ds_bpermute_b32 v89, v13, v89
	s_waitcnt lgkmcnt(8)
	v_lshl_add_u64 v[10:11], v[16:17], 0, v[8:9]
	global_store_dwordx4 v[16:17], v[158:161], off
	global_store_dwordx4 v[10:11], v[94:97], off
	v_cvt_pk_f16_f32 v154, v154, v155
	v_cvt_pk_f16_f32 v155, v156, v157
	v_cvt_pk_f16_f32 v156, v138, v139
	v_cvt_pk_f16_f32 v157, v140, v141
	v_cvt_pk_f16_f32 v90, v90, v91
	v_cvt_pk_f16_f32 v91, v92, v93
	v_cvt_pk_f16_f32 v92, v74, v75
	v_cvt_pk_f16_f32 v93, v76, v77
	v_mov_b32_dpp v0, v154 row_ror:8 row_mask:0xf bank_mask:0xf
	v_mov_b32_dpp v1, v155 row_ror:8 row_mask:0xf bank_mask:0xf
	v_mov_b32_dpp v2, v156 row_ror:8 row_mask:0xf bank_mask:0xf
	v_mov_b32_dpp v3, v157 row_ror:8 row_mask:0xf bank_mask:0xf
	v_mov_b32_dpp v4, v90 row_ror:8 row_mask:0xf bank_mask:0xf
	v_mov_b32_dpp v5, v91 row_ror:8 row_mask:0xf bank_mask:0xf
	v_mov_b32_dpp v6, v92 row_ror:8 row_mask:0xf bank_mask:0xf
	v_mov_b32_dpp v7, v93 row_ror:8 row_mask:0xf bank_mask:0xf
	v_cndmask_b32_e32 v154, v154, v4, vcc
	v_cndmask_b32_e32 v155, v155, v5, vcc
	v_cndmask_b32_e32 v156, v156, v6, vcc
	v_cndmask_b32_e32 v157, v157, v7, vcc
	v_cndmask_b32_e32 v90, v0, v90, vcc
	v_cndmask_b32_e32 v91, v1, v91, vcc
	v_cndmask_b32_e32 v92, v2, v92, vcc
	v_cndmask_b32_e32 v93, v3, v93, vcc
	ds_bpermute_b32 v154, v13, v154
	ds_bpermute_b32 v155, v13, v155
	ds_bpermute_b32 v156, v13, v156
	ds_bpermute_b32 v157, v13, v157
	ds_bpermute_b32 v90, v13, v90
	ds_bpermute_b32 v91, v13, v91
	ds_bpermute_b32 v92, v13, v92
	ds_bpermute_b32 v93, v13, v93
	s_waitcnt lgkmcnt(8)
	v_lshl_add_u64 v[10:11], v[18:19], 0, v[8:9]
	global_store_dwordx4 v[18:19], v[150:153], off
	global_store_dwordx4 v[10:11], v[86:89], off
	v_cvt_pk_f16_f32 v146, v146, v147
	v_cvt_pk_f16_f32 v147, v148, v149
	v_cvt_pk_f16_f32 v148, v130, v131
	v_cvt_pk_f16_f32 v149, v132, v133
	v_cvt_pk_f16_f32 v82, v82, v83
	v_cvt_pk_f16_f32 v83, v84, v85
	v_cvt_pk_f16_f32 v84, v66, v67
	v_cvt_pk_f16_f32 v85, v68, v69
	v_mov_b32_dpp v0, v146 row_ror:8 row_mask:0xf bank_mask:0xf
	v_mov_b32_dpp v1, v147 row_ror:8 row_mask:0xf bank_mask:0xf
	v_mov_b32_dpp v2, v148 row_ror:8 row_mask:0xf bank_mask:0xf
	v_mov_b32_dpp v3, v149 row_ror:8 row_mask:0xf bank_mask:0xf
	v_mov_b32_dpp v4, v82 row_ror:8 row_mask:0xf bank_mask:0xf
	v_mov_b32_dpp v5, v83 row_ror:8 row_mask:0xf bank_mask:0xf
	v_mov_b32_dpp v6, v84 row_ror:8 row_mask:0xf bank_mask:0xf
	v_mov_b32_dpp v7, v85 row_ror:8 row_mask:0xf bank_mask:0xf
	v_cndmask_b32_e32 v146, v146, v4, vcc
	v_cndmask_b32_e32 v147, v147, v5, vcc
	v_cndmask_b32_e32 v148, v148, v6, vcc
	v_cndmask_b32_e32 v149, v149, v7, vcc
	v_cndmask_b32_e32 v82, v0, v82, vcc
	v_cndmask_b32_e32 v83, v1, v83, vcc
	v_cndmask_b32_e32 v84, v2, v84, vcc
	v_cndmask_b32_e32 v85, v3, v85, vcc
	ds_bpermute_b32 v146, v13, v146
	ds_bpermute_b32 v147, v13, v147
	ds_bpermute_b32 v148, v13, v148
	ds_bpermute_b32 v149, v13, v149
	ds_bpermute_b32 v82, v13, v82
	ds_bpermute_b32 v83, v13, v83
	ds_bpermute_b32 v84, v13, v84
	ds_bpermute_b32 v85, v13, v85
	s_waitcnt lgkmcnt(8)
	v_lshl_add_u64 v[10:11], v[20:21], 0, v[8:9]
	global_store_dwordx4 v[20:21], v[154:157], off
	global_store_dwordx4 v[10:11], v[90:93], off
	v_cvt_pk_f16_f32 v126, v126, v127
	v_cvt_pk_f16_f32 v127, v128, v129
	v_cvt_pk_f16_f32 v128, v110, v111
	v_cvt_pk_f16_f32 v129, v112, v113
	v_cvt_pk_f16_f32 v62, v62, v63
	v_cvt_pk_f16_f32 v63, v64, v65
	v_cvt_pk_f16_f32 v64, v46, v47
	v_cvt_pk_f16_f32 v65, v48, v49
	v_mov_b32_dpp v0, v126 row_ror:8 row_mask:0xf bank_mask:0xf
	v_mov_b32_dpp v1, v127 row_ror:8 row_mask:0xf bank_mask:0xf
	v_mov_b32_dpp v2, v128 row_ror:8 row_mask:0xf bank_mask:0xf
	v_mov_b32_dpp v3, v129 row_ror:8 row_mask:0xf bank_mask:0xf
	v_mov_b32_dpp v4, v62 row_ror:8 row_mask:0xf bank_mask:0xf
	v_mov_b32_dpp v5, v63 row_ror:8 row_mask:0xf bank_mask:0xf
	v_mov_b32_dpp v6, v64 row_ror:8 row_mask:0xf bank_mask:0xf
	v_mov_b32_dpp v7, v65 row_ror:8 row_mask:0xf bank_mask:0xf
	v_cndmask_b32_e32 v126, v126, v4, vcc
	v_cndmask_b32_e32 v127, v127, v5, vcc
	v_cndmask_b32_e32 v128, v128, v6, vcc
	v_cndmask_b32_e32 v129, v129, v7, vcc
	v_cndmask_b32_e32 v62, v0, v62, vcc
	v_cndmask_b32_e32 v63, v1, v63, vcc
	v_cndmask_b32_e32 v64, v2, v64, vcc
	v_cndmask_b32_e32 v65, v3, v65, vcc
	ds_bpermute_b32 v126, v13, v126
	ds_bpermute_b32 v127, v13, v127
	ds_bpermute_b32 v128, v13, v128
	ds_bpermute_b32 v129, v13, v129
	ds_bpermute_b32 v62, v13, v62
	ds_bpermute_b32 v63, v13, v63
	ds_bpermute_b32 v64, v13, v64
	ds_bpermute_b32 v65, v13, v65
	s_waitcnt lgkmcnt(8)
	v_lshl_add_u64 v[10:11], v[22:23], 0, v[8:9]
	global_store_dwordx4 v[22:23], v[146:149], off
	global_store_dwordx4 v[10:11], v[82:85], off
	v_cvt_pk_f16_f32 v118, v118, v119
	v_cvt_pk_f16_f32 v119, v120, v121
	v_cvt_pk_f16_f32 v120, v102, v103
	v_cvt_pk_f16_f32 v121, v104, v105
	v_cvt_pk_f16_f32 v54, v54, v55
	v_cvt_pk_f16_f32 v55, v56, v57
	v_cvt_pk_f16_f32 v56, v38, v39
	v_cvt_pk_f16_f32 v57, v40, v41
	v_mov_b32_dpp v0, v118 row_ror:8 row_mask:0xf bank_mask:0xf
	v_mov_b32_dpp v1, v119 row_ror:8 row_mask:0xf bank_mask:0xf
	v_mov_b32_dpp v2, v120 row_ror:8 row_mask:0xf bank_mask:0xf
	v_mov_b32_dpp v3, v121 row_ror:8 row_mask:0xf bank_mask:0xf
	v_mov_b32_dpp v4, v54 row_ror:8 row_mask:0xf bank_mask:0xf
	v_mov_b32_dpp v5, v55 row_ror:8 row_mask:0xf bank_mask:0xf
	v_mov_b32_dpp v6, v56 row_ror:8 row_mask:0xf bank_mask:0xf
	v_mov_b32_dpp v7, v57 row_ror:8 row_mask:0xf bank_mask:0xf
	v_cndmask_b32_e32 v118, v118, v4, vcc
	v_cndmask_b32_e32 v119, v119, v5, vcc
	v_cndmask_b32_e32 v120, v120, v6, vcc
	v_cndmask_b32_e32 v121, v121, v7, vcc
	v_cndmask_b32_e32 v54, v0, v54, vcc
	v_cndmask_b32_e32 v55, v1, v55, vcc
	v_cndmask_b32_e32 v56, v2, v56, vcc
	v_cndmask_b32_e32 v57, v3, v57, vcc
	ds_bpermute_b32 v118, v13, v118
	ds_bpermute_b32 v119, v13, v119
	ds_bpermute_b32 v120, v13, v120
	ds_bpermute_b32 v121, v13, v121
	ds_bpermute_b32 v54, v13, v54
	ds_bpermute_b32 v55, v13, v55
	ds_bpermute_b32 v56, v13, v56
	ds_bpermute_b32 v57, v13, v57
	s_waitcnt lgkmcnt(8)
	v_lshl_add_u64 v[10:11], v[24:25], 0, v[8:9]
	global_store_dwordx4 v[24:25], v[126:129], off
	global_store_dwordx4 v[10:11], v[62:65], off
	v_cvt_pk_f16_f32 v122, v122, v123
	v_cvt_pk_f16_f32 v123, v124, v125
	v_cvt_pk_f16_f32 v124, v106, v107
	v_cvt_pk_f16_f32 v125, v108, v109
	v_cvt_pk_f16_f32 v58, v58, v59
	v_cvt_pk_f16_f32 v59, v60, v61
	v_cvt_pk_f16_f32 v60, v42, v43
	v_cvt_pk_f16_f32 v61, v44, v45
	v_mov_b32_dpp v0, v122 row_ror:8 row_mask:0xf bank_mask:0xf
	v_mov_b32_dpp v1, v123 row_ror:8 row_mask:0xf bank_mask:0xf
	v_mov_b32_dpp v2, v124 row_ror:8 row_mask:0xf bank_mask:0xf
	v_mov_b32_dpp v3, v125 row_ror:8 row_mask:0xf bank_mask:0xf
	v_mov_b32_dpp v4, v58 row_ror:8 row_mask:0xf bank_mask:0xf
	v_mov_b32_dpp v5, v59 row_ror:8 row_mask:0xf bank_mask:0xf
	v_mov_b32_dpp v6, v60 row_ror:8 row_mask:0xf bank_mask:0xf
	v_mov_b32_dpp v7, v61 row_ror:8 row_mask:0xf bank_mask:0xf
	v_cndmask_b32_e32 v122, v122, v4, vcc
	v_cndmask_b32_e32 v123, v123, v5, vcc
	v_cndmask_b32_e32 v124, v124, v6, vcc
	v_cndmask_b32_e32 v125, v125, v7, vcc
	v_cndmask_b32_e32 v58, v0, v58, vcc
	v_cndmask_b32_e32 v59, v1, v59, vcc
	v_cndmask_b32_e32 v60, v2, v60, vcc
	v_cndmask_b32_e32 v61, v3, v61, vcc
	ds_bpermute_b32 v122, v13, v122
	ds_bpermute_b32 v123, v13, v123
	ds_bpermute_b32 v124, v13, v124
	ds_bpermute_b32 v125, v13, v125
	ds_bpermute_b32 v58, v13, v58
	ds_bpermute_b32 v59, v13, v59
	ds_bpermute_b32 v60, v13, v60
	ds_bpermute_b32 v61, v13, v61
	s_waitcnt lgkmcnt(8)
	v_lshl_add_u64 v[10:11], v[26:27], 0, v[8:9]
	global_store_dwordx4 v[26:27], v[118:121], off
	global_store_dwordx4 v[10:11], v[54:57], off
	v_cvt_pk_f16_f32 v114, v114, v115
	v_cvt_pk_f16_f32 v115, v116, v117
	v_cvt_pk_f16_f32 v116, v98, v99
	v_cvt_pk_f16_f32 v117, v100, v101
	v_cvt_pk_f16_f32 v50, v50, v51
	v_cvt_pk_f16_f32 v51, v52, v53
	v_cvt_pk_f16_f32 v52, v34, v35
	v_cvt_pk_f16_f32 v53, v36, v37
	v_mov_b32_dpp v0, v114 row_ror:8 row_mask:0xf bank_mask:0xf
	v_mov_b32_dpp v1, v115 row_ror:8 row_mask:0xf bank_mask:0xf
	v_mov_b32_dpp v2, v116 row_ror:8 row_mask:0xf bank_mask:0xf
	v_mov_b32_dpp v3, v117 row_ror:8 row_mask:0xf bank_mask:0xf
	v_mov_b32_dpp v4, v50 row_ror:8 row_mask:0xf bank_mask:0xf
	v_mov_b32_dpp v5, v51 row_ror:8 row_mask:0xf bank_mask:0xf
	v_mov_b32_dpp v6, v52 row_ror:8 row_mask:0xf bank_mask:0xf
	v_mov_b32_dpp v7, v53 row_ror:8 row_mask:0xf bank_mask:0xf
	v_cndmask_b32_e32 v114, v114, v4, vcc
	v_cndmask_b32_e32 v115, v115, v5, vcc
	v_cndmask_b32_e32 v116, v116, v6, vcc
	v_cndmask_b32_e32 v117, v117, v7, vcc
	v_cndmask_b32_e32 v50, v0, v50, vcc
	v_cndmask_b32_e32 v51, v1, v51, vcc
	v_cndmask_b32_e32 v52, v2, v52, vcc
	v_cndmask_b32_e32 v53, v3, v53, vcc
	ds_bpermute_b32 v114, v13, v114
	ds_bpermute_b32 v115, v13, v115
	ds_bpermute_b32 v116, v13, v116
	ds_bpermute_b32 v117, v13, v117
	ds_bpermute_b32 v50, v13, v50
	ds_bpermute_b32 v51, v13, v51
	ds_bpermute_b32 v52, v13, v52
	ds_bpermute_b32 v53, v13, v53
	s_waitcnt lgkmcnt(8)
	v_lshl_add_u64 v[10:11], v[28:29], 0, v[8:9]
	global_store_dwordx4 v[28:29], v[122:125], off
	global_store_dwordx4 v[10:11], v[58:61], off
	s_waitcnt lgkmcnt(0)
	v_lshl_add_u64 v[10:11], v[30:31], 0, v[8:9]
	global_store_dwordx4 v[30:31], v[114:117], off
	global_store_dwordx4 v[10:11], v[50:53], off
	s_mov_b64 s[4:5], 0
